# DA rotation restricted to heads 0-3 (heads 4-7 keep 0..63 order so CUs sharing a K/V stream stay in step for L2)
# baseline (speedup 1.0000x reference)
; __device__ __forceinline__ int v_rd_base(int lane) { return ((lane & 3) << 3) | (((lane >> 2) & 3) << 6) | (((lane >> 4) & 1) << 5) | (((lane >> 5) & 1) << 8); }
; #define WAIT_BAR_0() asm volatile("s_waitcnt vmcnt(0) lgkmcnt(0)\n\ts_barrier" ::: "memory")
; #define WAIT_BAR_0() asm volatile("s_waitcnt vmcnt(0) lgkmcnt(0)\n\ts_barrier" ::: "memory")
; #define WAIT_BAR_0() asm volatile("s_waitcnt vmcnt(0) lgkmcnt(0)\n\ts_barrier" ::: "memory")
; #define lane mk_lane()
; __device__ __forceinline__ void attn_unit_da(const AttnUnit& U, char* lds) {
;     ...
;   const unsigned kdst = lds0 + A_OFF_K + wid * 1024, vdst = lds0 + A_OFF_V + wid * 1024;
;   const int vb0 = (int)lds0 + A_OFF_V + v_rd_base(lane);
;   const long kstep = (long)KVBLK * U.ldk, vstep = (long)KVBLK * U.ldv;
;     ...
;   f32x16 p0, p1; float mn = 0.f, al = 1.f; bf16x8 pa0, pa1, pa2, pa3; const int NT = U.NT;
;   DMA_TILE(0, 0);
;   WAIT_BAR_0();
; __global__ void __launch_bounds__(512, 2) fwd_kernel(Params p) {
;     ...
;             const int q_ = it & 15, mp = (it >> 4) & 1, b = (it >> 5) & 7, h = it >> 8, qb = (q_ + ((h < 4) ? ((0x084C >> (4 * h)) & 15) : 0)) & 15; const size_t r0 = (size_t)b * SEQ;
;             att::AttnUnit U{};
;             U.Q = QKV1 + (r0 + qb * 256) * 6144 + h * 256 + mp * 128; U.K = QKV1 + r0 * 6144 + 2048 + h * 256 + mp * 128; U.V = QKV1 + r0 * 6144 + 4096 + h * 256;
.LBB0_1934:
	s_or_b64 exec, exec, s[6:7]
	s_lshr_b32 s2, s8, 4
	s_and_b32 s2, s2, 1
	s_lshl_b32 s25, s2, 8
	s_mul_i32 s37, s37, 0x3000000
	s_lshl_b64 s[0:1], s[0:1], 1
	s_add_u32 s0, s37, s0
	s_addc_u32 s1, 0, s1
	s_add_u32 s0, s35, s0
	s_addc_u32 s1, s42, s1
	s_and_b32 s98, s66, 0xf00
	s_cmp_lt_i32 s65, 4
	s_cselect_b32 s98, s98, 0
	s_mul_i32 s98, s98, 0x3000
	s_add_u32 s0, s0, s98
	s_addc_u32 s1, s1, 0
	s_mulk_i32 s68, 0x3000
	s_add_u32 s2, s44, s68
	s_addc_u32 s3, s45, 0
	s_lshl_b32 s4, s24, 1
	s_add_u32 s5, s2, s18
	s_addc_u32 s6, s3, s19
	s_add_u32 s2, s5, s4
	s_addc_u32 s3, s6, 0
	s_add_u32 s2, s2, 0x1000
	s_addc_u32 s3, s3, 0
	s_add_u32 s4, s5, 0x2000
	s_addc_u32 s5, s6, 0
	s_add_u32 s2, s2, s98
	s_addc_u32 s3, s3, 0
	s_add_u32 s4, s4, s98
	s_addc_u32 s5, s5, 0
	s_lshl_b32 s6, s70, 2
	s_waitcnt lgkmcnt(1)
	v_mov_b32_e32 v6, v226
	s_add_i32 s24, s6, 0
	v_sub_u32_e32 v0, v0, v244
	s_add_i32 s24, s24, 0x18000
	v_bfe_u32 v8, v6, 4, 5
	v_cvt_f32_i32_e32 v130, v0
	s_lshl_b32 s37, s69, 10
	v_and_b32_e32 v0, 15, v6
	s_waitcnt lgkmcnt(0)
	v_lshrrev_b32_e32 v7, 4, v6
	v_lshlrev_b32_e32 v2, 2, v7
	v_bitop3_b32 v0, v2, v0, 12 bitop3:0x6c
	v_lshrrev_b32_e32 v2, 2, v7
	v_bitop3_b32 v0, v2, v0, 3 bitop3:0x6c
	v_mul_u32_u24_e32 v2, 0x1800, v8
	s_cmp_lg_u32 0, -1
	v_lshlrev_b32_e32 v2, 1, v2
	s_cselect_b32 s6, 0, 0
	v_lshl_or_b32 v0, v0, 4, v2
	s_add_i32 s37, s37, s6
	v_lshl_add_u64 v[2:3], s[2:3], 0, v[0:1]
	v_add_u32_e32 v0, 0x60000, v0
	s_add_i32 s38, s37, 0x10000
	s_mov_b32 s7, m0
	s_mov_b32 m0, s38
	s_nop 0
	global_load_lds_dwordx4 v[2:3], off
	s_mov_b32 m0, s7
	v_lshl_add_u64 v[2:3], s[2:3], 0, v[0:1]
	s_add_i32 s2, s37, 0x12000
	s_mov_b32 s3, m0
	s_mov_b32 m0, s2
	s_nop 0
	global_load_lds_dwordx4 v[2:3], off
	s_mov_b32 m0, s3
	v_and_b32_e32 v2, 0x60, v6
	v_lshlrev_b32_e32 v3, 3, v6
	v_and_or_b32 v9, v3, 24, v2
	v_lshrrev_b32_e32 v2, 1, v6
	v_lshrrev_b32_e32 v3, 5, v6
	v_bfe_u32 v0, v6, 2, 2
	v_and_b32_e32 v2, 8, v2
	v_and_b32_e32 v3, 4, v3
	v_or3_b32 v6, v3, v0, v2
	v_and_or_b32 v0, v7, 16, v6
	v_mul_u32_u24_e32 v0, 0x1800, v0
	v_or_b32_e32 v0, v0, v9
	v_or_b32_e32 v8, 32, v8
	v_lshlrev_b32_e32 v0, 1, v0
	v_lshl_add_u64 v[2:3], s[4:5], 0, v[0:1]
	v_and_or_b32 v0, v8, 48, v6
	v_mul_u32_u24_e32 v0, 0x1800, v0
	v_or_b32_e32 v0, v0, v9
	s_mov_b32 s2, m0
	s_mov_b32 m0, s37
	s_nop 0
	global_load_lds_dwordx4 v[2:3], off
	s_mov_b32 m0, s2
	v_lshl_add_u64 v[2:3], v[2:3], 0, s[22:23]
	v_lshlrev_b32_e32 v0, 1, v0
	s_add_i32 s2, s37, 0x4000
	s_mov_b32 s3, m0
	s_mov_b32 m0, s2
	s_nop 0
	global_load_lds_dwordx4 v[2:3], off
	s_mov_b32 m0, s3
	v_lshl_add_u64 v[2:3], s[4:5], 0, v[0:1]
	s_add_i32 s2, s37, 0x2000
	s_mov_b32 s3, m0
	s_mov_b32 m0, s2
	s_nop 0
	global_load_lds_dwordx4 v[2:3], off
	s_mov_b32 m0, s3
	v_lshl_add_u64 v[2:3], v[2:3], 0, s[22:23]
	s_add_i32 s2, s37, 0x6000
	s_mov_b32 s3, m0
	s_mov_b32 m0, s2
	s_nop 0
	global_load_lds_dwordx4 v[2:3], off
	s_mov_b32 m0, s3
	v_lshlrev_b32_e32 v2, 3, v243
	v_lshlrev_b32_e32 v3, 4, v243
	v_lshlrev_b32_e32 v239, 4, v5
	v_and_b32_e32 v6, 0xc0, v3
	v_and_b32_e32 v7, 0x118, v2
	v_lshlrev_b32_e32 v2, 2, v5
	v_lshlrev_b32_e32 v3, 6, v4
	v_and_b32_e32 v3, 0xc0, v3
	v_lshlrev_b32_e32 v14, 2, v4
	v_bitop3_b32 v3, v14, v3, 48 bitop3:0x6c
	v_add_u32_e32 v5, 32, v239
	v_bitop3_b32 v247, v5, v3, s60 bitop3:0x78
	v_add_u32_e32 v5, 64, v239
	v_bitop3_b32 v248, v5, v3, s60 bitop3:0x78
	v_add_u32_e32 v5, 0x60, v239
	v_bitop3_b32 v249, v5, v3, s60 bitop3:0x78
	v_add_u32_e32 v5, 0x80, v239
	v_bitop3_b32 v250, v5, v3, s60 bitop3:0x78
	v_add_u32_e32 v5, 0xa0, v239
	s_add_i32 s2, 0, 0x10000
	v_bitop3_b32 v252, v5, v3, s60 bitop3:0x78
	v_add_u32_e32 v5, 0xc0, v239
	v_lshlrev_b32_e32 v0, 1, v243
	v_bitop3_b32 v253, v5, v3, s60 bitop3:0x78
	v_add_u32_e32 v5, 0xe0, v239
	s_add_u32 s4, s54, s67
	v_bitop3_b32 v246, v3, v239, s60 bitop3:0x6c
	v_bitop3_b32 v254, v5, v3, s60 bitop3:0x78
	v_ashrrev_i32_e32 v3, 31, v2
	v_and_or_b32 v0, v0, 32, v7
	s_addc_u32 s5, s55, 0
	v_mov_b32_e32 v14, v1
	v_mov_b32_e32 v15, v1
	s_waitcnt vmcnt(0) lgkmcnt(0)
	s_barrier
; #define WAIT_BAR_0() asm volatile("s_waitcnt vmcnt(0) lgkmcnt(0)\n\ts_barrier" ::: "memory")
; #define WAIT_BAR_0() asm volatile("s_waitcnt vmcnt(0) lgkmcnt(0)\n\ts_barrier" ::: "memory")
; #define WAIT_BAR_0() asm volatile("s_waitcnt vmcnt(0) lgkmcnt(0)\n\ts_barrier" ::: "memory")
; __device__ __forceinline__ void attn_unit_da(const AttnUnit& U, char* lds) {
;     ...
;   f32x16 p0, p1; float mn = 0.f, al = 1.f; bf16x8 pa0, pa1, pa2, pa3; const int NT = U.NT;
;   DMA_TILE(0, 0);
;   WAIT_BAR_0();
;   for (int j = 0; j < NT; ++j) {
;     const int st = j & 1;
;     if (j + 1 < NT) DMA_TILE(j + 1, st ^ 1);
;     float rc;
;     { const int c_ = __builtin_amdgcn_readfirstlane(cls[j]); const float* ak_ = aux + j * KVBLK;
;       if (c_ < 2) { rc = (c_ == 0) ? pq * U.nsl : -pq * U.nsl;
	v_lshl_add_u32 v245, v4, 8, s2
	v_lshl_add_u32 v251, v4, 2, s24
	v_add3_u32 v237, v6, s6, v0
	v_lshl_add_u64 v[232:233], v[2:3], 2, s[4:5]
	v_mov_b32_e32 v0, v1
	v_mov_b32_e32 v2, v1
	v_mov_b32_e32 v3, v1
	v_mov_b32_e32 v4, v1
	v_mov_b32_e32 v5, v1
	v_mov_b32_e32 v6, v1
	v_mov_b32_e32 v7, v1
	v_mov_b32_e32 v8, v1
	v_mov_b32_e32 v9, v1
	v_mov_b32_e32 v10, v1
	v_mov_b32_e32 v11, v1
	v_mov_b32_e32 v12, v1
	v_mov_b32_e32 v13, v1
	v_mov_b64_e32 v[128:129], v[14:15]
	v_mov_b64_e32 v[112:113], v[14:15]
	v_mov_b64_e32 v[96:97], v[14:15]
	v_mov_b64_e32 v[80:81], v[14:15]
	v_mov_b64_e32 v[64:65], v[14:15]
	v_mov_b64_e32 v[48:49], v[14:15]
	v_mov_b64_e32 v[32:33], v[14:15]
	v_mov_b64_e32 v[126:127], v[12:13]
	v_mov_b64_e32 v[124:125], v[10:11]
	v_mov_b64_e32 v[122:123], v[8:9]
	v_mov_b64_e32 v[120:121], v[6:7]
	v_mov_b64_e32 v[118:119], v[4:5]
	v_mov_b64_e32 v[116:117], v[2:3]
	v_mov_b64_e32 v[114:115], v[0:1]
	v_mov_b64_e32 v[110:111], v[12:13]
	v_mov_b64_e32 v[108:109], v[10:11]
	v_mov_b64_e32 v[106:107], v[8:9]
	v_mov_b64_e32 v[104:105], v[6:7]
	v_mov_b64_e32 v[102:103], v[4:5]
	v_mov_b64_e32 v[100:101], v[2:3]
	v_mov_b64_e32 v[98:99], v[0:1]
	v_mov_b64_e32 v[94:95], v[12:13]
	v_mov_b64_e32 v[92:93], v[10:11]
	v_mov_b64_e32 v[90:91], v[8:9]
	v_mov_b64_e32 v[88:89], v[6:7]
	v_mov_b64_e32 v[86:87], v[4:5]
	v_mov_b64_e32 v[84:85], v[2:3]
	v_mov_b64_e32 v[82:83], v[0:1]
	v_mov_b64_e32 v[78:79], v[12:13]
	v_mov_b64_e32 v[76:77], v[10:11]
	v_mov_b64_e32 v[74:75], v[8:9]
	v_mov_b64_e32 v[72:73], v[6:7]
	v_mov_b64_e32 v[70:71], v[4:5]
	v_mov_b64_e32 v[68:69], v[2:3]
	v_mov_b64_e32 v[66:67], v[0:1]
	v_mov_b64_e32 v[62:63], v[12:13]
	v_mov_b64_e32 v[60:61], v[10:11]
	v_mov_b64_e32 v[58:59], v[8:9]
	v_mov_b64_e32 v[56:57], v[6:7]
	v_mov_b64_e32 v[54:55], v[4:5]
	v_mov_b64_e32 v[52:53], v[2:3]
	v_mov_b64_e32 v[50:51], v[0:1]
	v_mov_b64_e32 v[46:47], v[12:13]
	v_mov_b64_e32 v[44:45], v[10:11]
	v_mov_b64_e32 v[42:43], v[8:9]
	v_mov_b64_e32 v[40:41], v[6:7]
	v_mov_b64_e32 v[38:39], v[4:5]
	v_mov_b64_e32 v[36:37], v[2:3]
	v_mov_b64_e32 v[34:35], v[0:1]
	v_mov_b64_e32 v[30:31], v[12:13]
	v_mov_b64_e32 v[28:29], v[10:11]
	v_mov_b64_e32 v[26:27], v[8:9]
	v_mov_b64_e32 v[24:25], v[6:7]
	v_mov_b64_e32 v[22:23], v[4:5]
	v_mov_b64_e32 v[20:21], v[2:3]
	v_mov_b64_e32 v[18:19], v[0:1]
	v_mov_b64_e32 v[16:17], v[14:15]
	s_mov_b32 s36, 0
	v_cmp_gt_u32_e64 s[2:3], 32, v243
	v_mov_b32_e32 v230, v228
	v_mov_b32_e32 v231, v228
	v_mov_b32_e32 v131, v130
	v_mov_b32_e32 v132, v130
	v_mov_b32_e32 v133, v130
	v_mov_b32_e32 v134, v130
	v_mov_b32_e32 v135, v130
	v_mov_b32_e32 v136, v130
	v_mov_b32_e32 v137, v130
	v_mov_b32_e32 v138, v130
	v_mov_b32_e32 v139, v130
	v_mov_b32_e32 v140, v130
	v_mov_b32_e32 v141, v130
	v_mov_b32_e32 v142, v130
	v_mov_b32_e32 v240, 0
	v_mov_b32_e32 v238, 0xf149f2ca
	s_and_b32 s98, s66, 0xf00
	s_cmp_lt_i32 s65, 4
	s_cselect_b32 s98, s98, 0
	s_lshl_b32 s6, s98, 2
	s_mov_b32 s7, 0
	s_and_b32 s99, s66, 0xf00
	s_cmp_lt_i32 s65, 4
	s_cselect_b32 s99, s99, 0
	s_lshr_b32 s99, s99, 4
	s_add_i32 s39, s99, 0x1c800
	s_and_b32 s99, s66, 0xf00
	s_cmp_lt_i32 s65, 4
	s_cselect_b32 s99, s99, 0
	s_lshl_b32 s99, s99, 2
	v_add_u32_e32 v227, s99, v239
	v_mov_b32_e32 v143, v130
	v_mov_b32_e32 v144, v130
	v_mov_b32_e32 v145, v130
	v_mov_b64_e32 v[14:15], v[12:13]
	v_mov_b64_e32 v[12:13], v[10:11]
	v_mov_b64_e32 v[10:11], v[8:9]
	v_mov_b64_e32 v[8:9], v[6:7]
	v_mov_b64_e32 v[6:7], v[4:5]
	v_mov_b64_e32 v[4:5], v[2:3]
	v_mov_b64_e32 v[2:3], v[0:1]
	s_branch .LBB0_1938
